# no per-segment setprio in GEMM K-loops + one static s_setprio 1 for waves 4-7 for the duration of each GEMM phase
# baseline (speedup 1.0000x reference)
; #define PG8_LAS __attribute__((address_space(3)))
; template <class Epi, class Sched, bool ALIGN_EPI = false, bool SP2 = false>
; __device__ __forceinline__ void gemm_phase(PG8_LAS unsigned char* lds, const Gemm g, const Sched& S, const Epi& E) {
;     int tid_ = threadIdx.x; asm volatile("" : "+v"(tid_));
;     const int tid = tid_, wid = __builtin_amdgcn_readfirstlane(tid >> 6), lane = tid & 63, wr = wid >> 2, wc = wid & 3, fr = lane & 15, fq = lane >> 4;
.LBB0_256:
	s_or_b64 exec, exec, s[16:17]
	v_readfirstlane_b32 s2, v202
	s_nop 3
	s_cmp_lt_u32 s2, 0x100
	s_cbranch_scc1 .Lhp_skip0
	s_setprio 1

; #define PG8_STAGE(bufoff, gbase, voff) do { _Pragma("unroll") for (int _i = 0; _i < 2; ++_i) \
;         __builtin_amdgcn_global_load_lds((const unsigned*)((const char*)(gbase) + (voff)[_i]), (PG8_LAS unsigned*)(lds + (bufoff) + ldsw + _i * 8192), 16, 0, 0); } while (0)
; #define PG8_WAIT_V(n) asm volatile("s_waitcnt vmcnt(" #n ")" ::: "memory")
; template <class Epi, class Sched, bool ALIGN_EPI = false, bool SP2 = false>
; __device__ __forceinline__ void gemm_phase(PG8_LAS unsigned char* lds, const Gemm g, const Sched& S, const Epi& E) {
;     int tid_ = threadIdx.x; asm volatile("" : "+v"(tid_));
;     const int tid = tid_, wid = __builtin_amdgcn_readfirstlane(tid >> 6), lane = tid & 63, wr = wid >> 2, wc = wid & 3, fr = lane & 15, fq = lane >> 4;
;     const int K = g.K, nt = K / BK;
;     unsigned voffA[2], voffB[2];
; #pragma unroll
;     for (int i = 0; i < 2; ++i) { int R, C; stage_rc(tid * 16 + i * 8192, R, C); const int Rb = Epi::PERM ? ((R & ~31) + perm32(R & 31)) : R;
;         voffA[i] = (unsigned)(R * K + C) * 2u; voffB[i] = (unsigned)(Rb * K + C) * 2u; }
;     const size_t kstep = (size_t)(BK * 2);
;     const size_t hstep = (size_t)HALF * K * 2;
;     const size_t tstep = 2 * hstep;
;     const unsigned ldsw = (unsigned)wid * 1024u;
;     const int aoff = lds_byte(wr * 64 + fr, fq * 8), boff = lds_byte(wc * 32 + fr, fq * 8);
;     ...
;     Unit cur, nxt; int ui = 0;
;     if (!S.next(0, cur)) return;
;     f32x4 acc[2][2][4][2];
; #pragma unroll
;     for (int a = 0; a < 2; ++a)
; #pragma unroll
;         for (int b = 0; b < 2; ++b)
; #pragma unroll
;             for (int m = 0; m < 4; ++m)
; #pragma unroll
;                 for (int n = 0; n < 2; ++n) acc[a][b][m][n] = (f32x4){0.f, 0.f, 0.f, 0.f};
;     bf16x8 At[4][2], B0[2][2], B1[2][2];
;     const char* cA = (const char*)g.A + (size_t)cur.pm * tstep; const char* cB = (const char*)g.Bt + (size_t)cur.pn * tstep;
;     S.a_ready(cur);
;     if constexpr (SP2) {
;         PG8_STAGE(PG8_SB(0, 0), cB, voffB); PG8_STAGE(PG8_SB(0, 1), cB + hstep, voffB); PG8_STAGE(PG8_SA(0, 0), cA, voffA); PG8_STAGE(PG8_SA(0, 1), cA + hstep, voffA);
;         if (wr == 1) PG8_BAR;
;         PG8_WAIT_V(2); PG8_BAR;
;         PG8_STAGE(PG8_SB(1, 0), cB + kstep, voffB); PG8_STAGE(PG8_SA(1, 0), cA + kstep, voffA); PG8_STAGE(PG8_SB(1, 1), cB + hstep + kstep, voffB);
;         PG8_WAIT_V(6); PG8_BAR;
.Lhp_skip1:
	s_mov_b64 s[16:17], s[72:73]
	s_mov_b64 s[4:5], s[72:73]
	s_waitcnt lgkmcnt(0)
	s_barrier
	s_waitcnt vmcnt(3)
	v_mov_b32_e32 v18, v202
	v_readlane_b32 s4, v245, 45
	v_readlane_b32 s5, v245, 46
	s_andn2_b64 vcc, exec, s[4:5]
	v_readfirstlane_b32 s28, v18
	v_cndmask_b32_e64 v0, 0, 1, s[4:5]
	v_cmp_ne_u32_e64 s[40:41], 1, v0
	s_cbranch_vccnz .LBB0_621
	v_lshlrev_b32_e32 v0, 4, v18
	v_add_u32_e32 v2, 0x2000, v0
	v_ashrrev_i32_e32 v3, 31, v2
	v_lshrrev_b32_e32 v3, 22, v3
	v_add_u32_e32 v3, v2, v3
	v_ashrrev_i32_e32 v10, 10, v3
	v_mul_i32_i24_e32 v3, 0x400, v10
	v_sub_u32_e32 v2, v2, v3
	v_lshrrev_b32_e32 v3, 4, v2
	v_bitop3_b32 v2, v3, v2, 32 bitop3:0x6c
	v_ashrrev_i32_e32 v3, 31, v2
	v_lshrrev_b32_e32 v3, 26, v3
	v_add_u32_e32 v3, v2, v3
	v_ashrrev_i32_e32 v11, 6, v3
	v_and_b32_e32 v3, 0xc0, v3
	v_sub_u32_e32 v2, v2, v3
	v_ashrrev_i16_sdwa v2, v206, sext(v2) dst_sel:DWORD dst_unused:UNUSED_PAD src0_sel:DWORD src1_sel:BYTE_0
	v_bfe_i32 v13, v2, 0, 16
	v_bfe_i32 v2, v18, 27, 1
	v_lshrrev_b32_e32 v2, 22, v2
	s_load_dwordx2 s[24:25], s[16:17], 0x80
	v_add_u32_e32 v2, v0, v2
	v_and_b32_e32 v2, 0xfffffc00, v2
	v_sub_u32_e32 v0, v0, v2
	v_lshrrev_b32_e32 v2, 4, v0
	v_bitop3_b32 v0, v2, v0, 32 bitop3:0x6c
	v_ashrrev_i32_e32 v3, 31, v18
	s_waitcnt lgkmcnt(0)
	s_add_u32 s29, s24, 0x16400000
	v_lshlrev_b32_e32 v4, 3, v10
	v_ashrrev_i32_e32 v2, 31, v0
	v_lshrrev_b32_e32 v3, 26, v3
	s_addc_u32 s34, s25, 0
	v_and_b32_e32 v4, 0xffff0, v4
	v_lshlrev_b32_e32 v5, 5, v10
	v_lshrrev_b32_e32 v2, 26, v2
	v_add_u32_e32 v3, v18, v3
	s_add_u32 s35, s24, 0x1c00000
	v_add_u32_e32 v4, v11, v4
	v_and_b32_e32 v12, 32, v5
	v_add_u32_e32 v2, v0, v2
	v_ashrrev_i32_e32 v15, 6, v3
	s_addc_u32 s47, s25, 0
	s_ashr_i32 s2, s28, 6
	v_lshl_or_b32 v4, v4, 11, v12
	v_ashrrev_i32_e32 v14, 6, v2
	v_lshlrev_b32_e32 v3, 3, v15
	v_and_b32_e32 v2, 0xc0, v2
	s_ashr_i32 s4, s28, 8
	s_lshl_b32 s60, s2, 10
	v_add_lshl_u32 v142, v4, v13, 1
	v_and_b32_e32 v3, 0xffff0, v3
	v_lshlrev_b32_e32 v4, 5, v15
	v_sub_u32_e32 v0, v0, v2
	v_readlane_b32 s8, v244, 10
	v_add_u32_e32 v3, v14, v3
	v_and_b32_e32 v16, 32, v4
	v_ashrrev_i16_sdwa v0, v206, sext(v0) dst_sel:DWORD dst_unused:UNUSED_PAD src0_sel:DWORD src1_sel:BYTE_0
	v_readlane_b32 s9, v244, 11
	s_add_u32 s18, s35, s8
	v_lshl_or_b32 v3, v3, 11, v16
	v_bfe_i32 v17, v0, 0, 16
	s_addc_u32 s19, s47, s9
	s_add_i32 s61, s60, 0
	v_add_lshl_u32 v0, v3, v17, 1
	s_add_i32 m0, s61, 0x10000
	v_mov_b32_e32 v143, v1
	global_load_lds_dwordx4 v0, s[18:19]
	s_add_i32 m0, s61, 0x12000
	s_add_u32 s8, s18, 0x80000
	global_load_lds_dwordx4 v142, s[18:19]
	s_addc_u32 s9, s19, 0
	s_add_i32 m0, s61, 0x14000
	v_lshl_add_u64 v[8:9], s[18:19], 0, v[0:1]
	global_load_lds_dwordx4 v0, s[8:9]
	s_add_i32 m0, s61, 0x16000
	v_lshl_add_u64 v[6:7], s[18:19], 0, v[142:143]
	global_load_lds_dwordx4 v142, s[8:9]
	v_readlane_b32 s8, v244, 32
	v_readlane_b32 s9, v244, 33
	s_add_u32 s16, s29, s8
	s_addc_u32 s17, s34, s9
	s_add_i32 s62, s61, 0x2000
	s_mov_b32 m0, s61
	s_add_u32 s8, s16, 0x80000
	global_load_lds_dwordx4 v0, s[16:17]
	s_mov_b32 m0, s62
	s_addc_u32 s9, s17, 0
	s_add_i32 s63, s61, 0x4000
	global_load_lds_dwordx4 v142, s[16:17]
	s_mov_b32 m0, s63
	s_add_i32 s64, s61, 0x6000
	global_load_lds_dwordx4 v0, s[8:9]
	s_mov_b32 m0, s64
	v_lshl_add_u64 v[4:5], s[16:17], 0, v[0:1]
	global_load_lds_dwordx4 v142, s[8:9]
	s_cmp_lg_u32 s4, 1
	v_lshl_add_u64 v[2:3], s[16:17], 0, v[142:143]
	s_cbranch_scc1 .LBB0_592
	s_barrier

; __device__ __forceinline__ void xcd_barrier(const XcdBarrier& b) {
;     asm volatile("s_waitcnt vmcnt(0)" ::: "memory");
;     __syncthreads();
;     if (threadIdx.x == 0) {
;         unsigned* bar = b.bar;
;         __builtin_amdgcn_s_waitcnt(0);
;         unsigned nloc = b.st[0], nx = b.st[1];
;         if (nloc == 0u) { xcd_barrier_complete(bar, b.x, nloc, nx); b.st[0] = nloc; b.st[1] = nx; }
.LBB0_621:
	s_setprio 0
	s_waitcnt vmcnt(0)
	s_waitcnt lgkmcnt(0)
	s_barrier
	s_and_saveexec_b64 s[16:17], s[78:79]
	s_cbranch_execz .LBB0_673
	v_readlane_b32 s2, v244, 22
	s_waitcnt vmcnt(0) expcnt(0) lgkmcnt(0)
	s_nop 0
	v_mov_b32_e32 v0, s2
	ds_read_b32 v3, v0
	v_readlane_b32 s2, v244, 23
	s_waitcnt lgkmcnt(0)
	v_cmp_ne_u32_e32 vcc, 0, v3
	v_mov_b32_e32 v0, s2
	ds_read_b32 v2, v0
	s_cbranch_vccnz .LBB0_637
	s_mov_b32 s2, 1
	s_branch .LBB0_625

; #define PG8_STAGE(bufoff, gbase, voff) do { _Pragma("unroll") for (int _i = 0; _i < 2; ++_i) \
;         __builtin_amdgcn_global_load_lds((const unsigned*)((const char*)(gbase) + (voff)[_i]), (PG8_LAS unsigned*)(lds + (bufoff) + ldsw + _i * 8192), 16, 0, 0); } while (0)
; #define PG8_WAIT_V(n) asm volatile("s_waitcnt vmcnt(" #n ")" ::: "memory")
; template <class Epi, class Sched, bool ALIGN_EPI = false, bool SP2 = false>
; __device__ __forceinline__ void gemm_phase(PG8_LAS unsigned char* lds, const Gemm g, const Sched& S, const Epi& E) {
;     int tid_ = threadIdx.x; asm volatile("" : "+v"(tid_));
;     const int tid = tid_, wid = __builtin_amdgcn_readfirstlane(tid >> 6), lane = tid & 63, wr = wid >> 2, wc = wid & 3, fr = lane & 15, fq = lane >> 4;
;     const int K = g.K, nt = K / BK;
;     unsigned voffA[2], voffB[2];
; #pragma unroll
;     for (int i = 0; i < 2; ++i) { int R, C; stage_rc(tid * 16 + i * 8192, R, C); const int Rb = Epi::PERM ? ((R & ~31) + perm32(R & 31)) : R;
;         voffA[i] = (unsigned)(R * K + C) * 2u; voffB[i] = (unsigned)(Rb * K + C) * 2u; }
;     const size_t kstep = (size_t)(BK * 2);
;     const size_t hstep = (size_t)HALF * K * 2;
;     const size_t tstep = 2 * hstep;
;     const unsigned ldsw = (unsigned)wid * 1024u;
;     const int aoff = lds_byte(wr * 64 + fr, fq * 8), boff = lds_byte(wc * 32 + fr, fq * 8);
;     ...
;     Unit cur, nxt; int ui = 0;
;     if (!S.next(0, cur)) return;
;     f32x4 acc[2][2][4][2];
; #pragma unroll
;     for (int a = 0; a < 2; ++a)
; #pragma unroll
;         for (int b = 0; b < 2; ++b)
; #pragma unroll
;             for (int m = 0; m < 4; ++m)
; #pragma unroll
;                 for (int n = 0; n < 2; ++n) acc[a][b][m][n] = (f32x4){0.f, 0.f, 0.f, 0.f};
;     bf16x8 At[4][2], B0[2][2], B1[2][2];
;     const char* cA = (const char*)g.A + (size_t)cur.pm * tstep; const char* cB = (const char*)g.Bt + (size_t)cur.pn * tstep;
;     S.a_ready(cur);
;     if constexpr (SP2) {
;         PG8_STAGE(PG8_SB(0, 0), cB, voffB); PG8_STAGE(PG8_SB(0, 1), cB + hstep, voffB); PG8_STAGE(PG8_SA(0, 0), cA, voffA); PG8_STAGE(PG8_SA(0, 1), cA + hstep, voffA);
;         if (wr == 1) PG8_BAR;
;         PG8_WAIT_V(2); PG8_BAR;
;         PG8_STAGE(PG8_SB(1, 0), cB + kstep, voffB); PG8_STAGE(PG8_SA(1, 0), cA + kstep, voffA); PG8_STAGE(PG8_SB(1, 1), cB + hstep + kstep, voffB);
;         PG8_WAIT_V(6); PG8_BAR;
.Lhp_skip3:
	s_mov_b64 s[16:17], s[72:73]
	s_mov_b64 s[26:27], s[72:73]
	v_mov_b32_e32 v18, v202
	s_waitcnt lgkmcnt(0)
	s_barrier
	s_and_b64 vcc, exec, s[40:41]
	v_readfirstlane_b32 s28, v18
	v_readlane_b32 s13, v244, 49
	s_cbranch_vccnz .LBB0_921
	v_lshlrev_b32_e32 v0, 4, v18
	v_add_u32_e32 v2, 0x2000, v0
	v_ashrrev_i32_e32 v3, 31, v2
	v_lshrrev_b32_e32 v3, 22, v3
	v_add_u32_e32 v3, v2, v3
	v_ashrrev_i32_e32 v10, 10, v3
	v_mul_i32_i24_e32 v3, 0x400, v10
	v_sub_u32_e32 v2, v2, v3
	v_lshrrev_b32_e32 v3, 4, v2
	v_bitop3_b32 v2, v3, v2, 32 bitop3:0x6c
	v_ashrrev_i32_e32 v3, 31, v2
	v_lshrrev_b32_e32 v3, 26, v3
	v_add_u32_e32 v3, v2, v3
	v_ashrrev_i32_e32 v11, 6, v3
	v_and_b32_e32 v3, 0xc0, v3
	v_sub_u32_e32 v2, v2, v3
	v_ashrrev_i16_sdwa v2, v206, sext(v2) dst_sel:DWORD dst_unused:UNUSED_PAD src0_sel:DWORD src1_sel:BYTE_0
	v_bfe_i32 v13, v2, 0, 16
	v_bfe_i32 v2, v18, 27, 1
	v_lshrrev_b32_e32 v2, 22, v2
	s_load_dwordx2 s[24:25], s[16:17], 0x80
	v_add_u32_e32 v2, v0, v2
	v_and_b32_e32 v2, 0xfffffc00, v2
	v_sub_u32_e32 v0, v0, v2
	v_lshrrev_b32_e32 v2, 4, v0
	v_bitop3_b32 v0, v2, v0, 32 bitop3:0x6c
	v_ashrrev_i32_e32 v3, 31, v18
	s_waitcnt lgkmcnt(0)
	s_add_u32 s29, s24, 0xa400000
	v_lshlrev_b32_e32 v4, 3, v10
	v_ashrrev_i32_e32 v2, 31, v0
	v_lshrrev_b32_e32 v3, 26, v3
	s_addc_u32 s34, s25, 0
	v_and_b32_e32 v4, 0x3fff0, v4
	v_lshlrev_b32_e32 v5, 5, v10
	v_lshrrev_b32_e32 v2, 26, v2
	v_add_u32_e32 v3, v18, v3
	s_add_u32 s35, s24, 0x4400000
	v_add_u32_e32 v4, v11, v4
	v_and_b32_e32 v12, 32, v5
	v_add_u32_e32 v2, v0, v2
	v_ashrrev_i32_e32 v15, 6, v3
	s_addc_u32 s62, s25, 0
	s_ashr_i32 s2, s28, 6
	v_lshl_or_b32 v4, v4, 13, v12
	v_ashrrev_i32_e32 v14, 6, v2
	v_lshlrev_b32_e32 v3, 3, v15
	v_and_b32_e32 v2, 0xc0, v2
	s_ashr_i32 s4, s28, 8
	s_lshl_b32 s63, s2, 10
	v_add_lshl_u32 v142, v4, v13, 1
	v_and_b32_e32 v3, 0x3fff0, v3
	v_lshlrev_b32_e32 v4, 5, v15
	v_sub_u32_e32 v0, v0, v2
	v_readlane_b32 s8, v244, 12
	v_add_u32_e32 v3, v14, v3
	v_and_b32_e32 v16, 32, v4
	v_ashrrev_i16_sdwa v0, v206, sext(v0) dst_sel:DWORD dst_unused:UNUSED_PAD src0_sel:DWORD src1_sel:BYTE_0
	v_readlane_b32 s9, v244, 13
	s_add_u32 s18, s35, s8
	v_lshl_or_b32 v3, v3, 13, v16
	v_bfe_i32 v17, v0, 0, 16
	s_addc_u32 s19, s62, s9
	s_add_i32 s64, s63, 0
	v_add_lshl_u32 v0, v3, v17, 1
	s_add_i32 m0, s64, 0x10000
	s_load_dwordx2 s[48:49], s[26:27], 0x78
	global_load_lds_dwordx4 v0, s[18:19]
	s_add_i32 m0, s64, 0x12000
	s_add_u32 s8, s18, 0x200000
	global_load_lds_dwordx4 v142, s[18:19]
	s_addc_u32 s9, s19, 0
	s_add_i32 m0, s64, 0x14000
	v_mov_b32_e32 v143, v1
	global_load_lds_dwordx4 v0, s[8:9]
	s_add_i32 m0, s64, 0x16000
	v_lshl_add_u64 v[8:9], s[18:19], 0, v[0:1]
	global_load_lds_dwordx4 v142, s[8:9]
	v_readlane_b32 s8, v244, 36
	v_readlane_b32 s9, v244, 37
	s_add_u32 s16, s29, s8
	s_addc_u32 s17, s34, s9
	s_add_i32 s65, s64, 0x2000
	s_mov_b32 m0, s64
	s_add_u32 s8, s16, 0x200000
	global_load_lds_dwordx4 v0, s[16:17]
	s_mov_b32 m0, s65
	s_addc_u32 s9, s17, 0
	s_add_i32 s66, s64, 0x4000
	global_load_lds_dwordx4 v142, s[16:17]
	s_mov_b32 m0, s66
	s_add_i32 s67, s64, 0x6000
	global_load_lds_dwordx4 v0, s[8:9]
	s_mov_b32 m0, s67
	v_lshl_add_u64 v[6:7], s[18:19], 0, v[142:143]
	global_load_lds_dwordx4 v142, s[8:9]
	v_lshl_add_u64 v[4:5], s[16:17], 0, v[0:1]
	s_cmp_lg_u32 s4, 1
	v_lshl_add_u64 v[2:3], s[16:17], 0, v[142:143]
	s_cbranch_scc1 .LBB0_748
	s_barrier

; #define GSYNC() xcd_barrier(xbar)
; __device__ __forceinline__ void xcd_barrier(const XcdBarrier& b) {
;     asm volatile("s_waitcnt vmcnt(0)" ::: "memory");
;     __syncthreads();
;     if (threadIdx.x == 0) {
;         unsigned* bar = b.bar;
;         __builtin_amdgcn_s_waitcnt(0);
;         unsigned nloc = b.st[0], nx = b.st[1];
;         if (nloc == 0u) { xcd_barrier_complete(bar, b.x, nloc, nx); b.st[0] = nloc; b.st[1] = nx; }
; __global__ void __launch_bounds__(512, 2) mega_fwd(Args args) {
;     ...
;         if (L == 0) GSYNC();
.LBB0_921:
	s_setprio 0
	v_readlane_b32 s4, v244, 50
	v_readlane_b32 s5, v244, 51
	s_andn2_b64 vcc, exec, s[4:5]
	s_mov_b64 s[16:17], -1
	s_cbranch_vccnz .LBB0_8
	s_waitcnt vmcnt(0)
	s_waitcnt lgkmcnt(0)
	s_barrier
	s_and_saveexec_b64 s[14:15], s[78:79]
	s_cbranch_execz .LBB0_7
	v_readlane_b32 s2, v244, 22
	s_waitcnt vmcnt(0) expcnt(0) lgkmcnt(0)
	s_nop 0
	v_mov_b32_e32 v0, s2
	ds_read_b32 v3, v0
	v_readlane_b32 s2, v244, 23
	s_waitcnt lgkmcnt(0)
	v_cmp_ne_u32_e32 vcc, 0, v3
	v_mov_b32_e32 v0, s2
	ds_read_b32 v2, v0
	s_cbranch_vccnz .LBB0_938
	s_mov_b32 s2, 1
	s_branch .LBB0_926
